# attention tile loops (mixer A and B): 63 compiler-packed v_pk_add/mul_f32 split into scalar pairs (bit-identical; packed fp32 stalls issue beside MFMAs)
# speedup vs baseline: 1.0083x; 1.0083x over previous
; DI float shflx(float v, int mask, int lane) { return __int_as_float(__builtin_amdgcn_ds_bpermute((lane ^ mask) << 2, __float_as_int(v))); }
; #define MFMA32(a, b, c) __builtin_amdgcn_mfma_f32_32x32x16_bf16((a), (b), (c), 0, 0, 0)
; template <bool MASKED>
; DI void attnB_tile_math(const f32x16& S, int kpos0, int kvalid, int qpos, int h, int lane, float& later, unsigned (&pw)[8]) {
;     ...
;     for (int r = 0; r < 16; ++r) {
;         const float x = S[r] * scale2; x2[r] = x;
;         const float e = __builtin_amdgcn_exp2f(-fabsf(x));
;         const float v = fmaxf(x, 0.f) + __builtin_amdgcn_logf(1.0f + e);
;         if (MASKED) { const int row = (r & 3) + 8 * (r >> 2) + 4 * h; const bool vis = (row < kvalid) && (kpos0 + row < qpos); sp[r] = vis ? v : 0.f; }
;         else sp[r] = v;
;     }
;     float G[4], P[4];
; #pragma unroll
;     for (int g = 0; g < 4; ++g) { G[g] = (sp[4 * g] + sp[4 * g + 1]) + (sp[4 * g + 2] + sp[4 * g + 3]); P[g] = shflx(G[g], 32, lane); }
;     float R[4]; R[3] = 0.f; R[2] = G[3] + P[3]; R[1] = R[2] + (G[2] + P[2]); R[0] = R[1] + (G[1] + P[1]);
;     const float total = R[0] + (G[0] + P[0]);
; DI void attnB_item(bf16_t* z, int hh, int qs, LAS bf16_t* vs, int lane) {
;     ...
;         f32x16 S; bf16x8 qf[8];
; #pragma unroll
;         for (int i = 0; i < 16; ++i) S[i] = 0.f;
; #pragma unroll
;         for (int s = 0; s < 8; ++s) qf[s] = qs_lds[64 * s];
;         asm volatile("s_waitcnt lgkmcnt(0)" ::: "memory"); __builtin_amdgcn_sched_barrier(0);
;         __builtin_amdgcn_s_setprio(1);
; #pragma unroll
;         for (int s = 0; s < 8; ++s) S = MFMA32(kf[s], qf[s], S);
;         __builtin_amdgcn_s_setprio(0);
; #pragma unroll
;         for (int s = 0; s < 8; ++s) kf[s] = *(const bf16x8*)(kbase + ron + (((s >> 1) << 9) | ((s & 1) << 8)));
.LBB0_151:
	s_waitcnt vmcnt(8)
	v_mov_b64_e32 v[148:149], v[144:145]
	v_mov_b64_e32 v[146:147], v[142:143]
	s_cmp_lt_i32 s30, 0
	ds_read_b128 v[66:69], v182 offset:10240
	ds_read_b128 v[142:145], v182 offset:11264
	ds_read_b128 v[150:153], v182 offset:12288
	ds_read_b128 v[192:195], v182 offset:13312
	ds_read_b128 v[196:199], v182 offset:14336
	ds_read_b128 v[200:203], v182 offset:15360
	ds_read_b128 v[204:207], v182 offset:16384
	ds_read_b128 v[208:211], v182 offset:17408
	s_cselect_b64 s[8:9], -1, 0
	s_cmp_gt_i32 s30, -1
	s_cselect_b64 s[4:5], -1, 0
	s_max_i32 s29, s30, 0
	s_add_i32 s29, s29, -1
	s_lshl_b32 s6, s29, 5
	s_cmp_gt_i32 s30, 0
	s_cselect_b32 s10, s6, 0x4000
	s_ashr_i32 s6, s10, 3
	s_lshl_b32 s11, s10, 8
	s_lshl_b32 s31, s10, 9
	s_andn2_b32 s6, s6, 31
	s_and_b32 s11, s11, 0x8000
	s_and_b32 s31, s31, 0x4000
	s_lshl_b32 s10, s10, 5
	s_waitcnt lgkmcnt(0)
	s_ashr_i32 s7, s6, 31
	s_or_b32 s11, s11, s31
	s_and_b32 s10, s10, 0x800
	s_or_b32 s10, s11, s10
	s_lshl_b64 s[6:7], s[6:7], 16
	s_setprio 1
	s_or_b32 s6, s6, s10
	s_waitcnt lgkmcnt(7)
	v_mfma_f32_32x32x16_bf16 v[66:81], v[114:117], v[66:69], 0
	s_cmp_lg_u32 s30, s28
	s_cselect_b64 s[10:11], -1, 0
	s_and_b64 s[38:39], s[10:11], s[4:5]
	s_mov_b64 s[10:11], -1
	v_add_f32_e32 v191, 0, v189
	s_and_b64 vcc, exec, s[38:39]
	s_waitcnt lgkmcnt(6)
	v_mfma_f32_32x32x16_bf16 v[66:81], v[118:121], v[142:145], v[66:81]
	v_lshl_add_u64 v[142:143], s[6:7], 1, v[158:159]
	s_waitcnt lgkmcnt(5)
	v_mfma_f32_32x32x16_bf16 v[66:81], v[122:125], v[150:153], v[66:81]
	s_waitcnt lgkmcnt(4)
	v_mfma_f32_32x32x16_bf16 v[66:81], v[126:129], v[192:195], v[66:81]
	s_waitcnt lgkmcnt(3)
	v_mfma_f32_32x32x16_bf16 v[66:81], v[130:133], v[196:199], v[66:81]
	s_waitcnt lgkmcnt(2)
	v_mfma_f32_32x32x16_bf16 v[66:81], v[134:137], v[200:203], v[66:81]
	global_load_dwordx4 v[114:117], v[142:143], off
	global_load_dwordx4 v[118:121], v[142:143], off offset:512
	global_load_dwordx4 v[122:125], v[142:143], off offset:1024
	global_load_dwordx4 v[126:129], v[142:143], off offset:1536
	global_load_dwordx4 v[130:133], v[142:143], off offset:2048
	global_load_dwordx4 v[134:137], v[142:143], off offset:2560
	s_waitcnt lgkmcnt(1)
	v_mfma_f32_32x32x16_bf16 v[66:81], v[138:141], v[204:207], v[66:81]
	global_load_dwordx4 v[138:141], v[142:143], off offset:3072
	s_nop 0
	global_load_dwordx4 v[142:145], v[142:143], off offset:3584
	s_waitcnt lgkmcnt(0)
	v_mfma_f32_32x32x16_bf16 v[66:81], v[146:149], v[208:211], v[66:81]
	s_setprio 0
	s_nop 11
	v_mul_f32_e32 v207, 0x3e0293ee, v66
	v_mul_f32_e32 v206, 0x3e0293ee, v67
	v_mul_f32_e32 v205, 0x3e0293ee, v68
	v_mul_f32_e32 v204, 0x3e0293ee, v69
	v_mul_f32_e32 v203, 0x3e0293ee, v70
	v_mul_f32_e32 v202, 0x3e0293ee, v71
	v_mul_f32_e32 v201, 0x3e0293ee, v72
	v_mul_f32_e32 v200, 0x3e0293ee, v73
	v_mul_f32_e32 v199, 0x3e0293ee, v74
	v_mul_f32_e32 v198, 0x3e0293ee, v75
	v_mul_f32_e32 v197, 0x3e0293ee, v76
	v_mul_f32_e32 v196, 0x3e0293ee, v77
	v_mul_f32_e32 v195, 0x3e0293ee, v78
	v_mul_f32_e32 v194, 0x3e0293ee, v79
	v_mul_f32_e32 v193, 0x3e0293ee, v80
	v_mul_f32_e32 v192, 0x3e0293ee, v81
	s_cbranch_vccz .LBB0_153
	v_exp_f32_e64 v147, -|v206|
	v_max_f32_e32 v149, 0, v206
	v_exp_f32_e64 v151, -|v205|
	v_max_f32_e32 v214, 0, v203
	v_add_f32_e32 v147, 1.0, v147
	v_log_f32_e32 v147, v147
	v_max_f32_e32 v215, 0, v202
	v_exp_f32_e64 v148, -|v207|
	v_max_f32_e32 v218, 0, v201
	v_add_f32_e32 v150, v149, v147
	v_exp_f32_e64 v147, -|v204|
	v_add_f32_e32 v149, 1.0, v151
	v_log_f32_e32 v208, v149
	v_exp_f32_e64 v149, -|v203|
	v_add_f32_e32 v147, 1.0, v147
	v_log_f32_e32 v212, v147
	v_exp_f32_e64 v147, -|v202|
	v_add_f32_e32 v149, 1.0, v149
	v_log_f32_e32 v216, v149
	v_exp_f32_e64 v149, -|v200|
	v_add_f32_e32 v147, 1.0, v147
	v_log_f32_e32 v217, v147
	v_exp_f32_e64 v147, -|v201|
	v_add_f32_e32 v148, 1.0, v148
	v_max_f32_e32 v219, 0, v200
	v_add_f32_e32 v214, v214, v216
	v_add_f32_e32 v215, v215, v217
	v_add_f32_e32 v147, 1.0, v147
	v_log_f32_e32 v216, v147
	v_add_f32_e32 v147, 1.0, v149
	v_log_f32_e32 v217, v147
	v_exp_f32_e64 v147, -|v199|
	v_exp_f32_e64 v149, -|v198|
	v_log_f32_e32 v148, v148
	v_add_f32_e32 v216, v218, v216
	v_add_f32_e32 v217, v219, v217
	v_add_f32_e32 v147, 1.0, v147
	v_log_f32_e32 v220, v147
	v_add_f32_e32 v147, 1.0, v149
	v_exp_f32_e64 v149, -|v197|
	v_log_f32_e32 v224, v147
	v_exp_f32_e64 v147, -|v196|
	v_max_f32_e32 v218, 0, v199
	v_add_f32_e32 v149, 1.0, v149
	v_log_f32_e32 v221, v149
	v_add_f32_e32 v147, 1.0, v147
	v_exp_f32_e64 v149, -|v195|
	v_log_f32_e32 v225, v147
	v_exp_f32_e64 v147, -|v194|
	v_max_f32_e32 v222, 0, v198
	v_add_f32_e32 v149, 1.0, v149
	v_log_f32_e32 v228, v149
	v_add_f32_e32 v147, 1.0, v147
	v_exp_f32_e64 v149, -|v193|
	v_log_f32_e32 v232, v147
	v_exp_f32_e64 v147, -|v192|
	v_max_f32_e32 v219, 0, v197
	v_add_f32_e32 v149, 1.0, v149
	v_log_f32_e32 v229, v149
	v_add_f32_e32 v147, 1.0, v147
	v_log_f32_e32 v233, v147
	v_max_f32_e32 v223, 0, v196
	v_max_f32_e32 v226, 0, v195
	v_max_f32_e32 v230, 0, v194
	v_max_f32_e32 v227, 0, v193
	v_max_f32_e32 v231, 0, v192
	v_add_f32_e32 v218, v218, v220
	v_add_f32_e32 v219, v219, v221
	v_add_f32_e32 v220, v222, v224
	v_add_f32_e32 v221, v223, v225
	v_add_f32_e32 v224, v226, v228
	v_add_f32_e32 v225, v227, v229
	v_add_f32_e32 v226, v230, v232
	v_add_f32_e32 v227, v231, v233
	v_add_f32_e32 v234, v214, v214
	v_add_f32_e32 v235, v214, v215
	v_add_f32_e32 v236, v216, v216
	v_add_f32_e32 v237, v216, v217
	v_add_f32_e32 v222, v218, v220
	v_add_f32_e32 v223, v219, v221
	v_add_f32_e32 v228, v224, v226
	v_add_f32_e32 v229, v225, v227
	v_max_f32_e32 v146, 0, v207
	v_add_f32_e32 v222, v222, v223
	v_mov_b32_e32 v223, v222
	v_add_f32_e32 v228, v228, v229
	v_mov_b32_e32 v229, v228
	v_mov_b32_e32 v147, v235
	v_mov_b32_e32 v149, v237
	ds_bpermute_b32 v209, v184, v222
	ds_bpermute_b32 v213, v184, v228
	v_add_f32_e32 v146, v146, v148
	v_add_f32_e32 v147, v147, v149
	ds_bpermute_b32 v151, v184, v147
	v_max_f32_e32 v152, 0, v205
	v_max_f32_e32 v210, 0, v204
	v_mov_b32_e32 v211, v228
	v_mov_b32_e32 v153, v222
	s_waitcnt lgkmcnt(1)
; DI unsigned pk2(float a, float b) { f32x2 v = {a, b}; bf16v2 r = __builtin_convertvector(v, bf16v2); return __builtin_bit_cast(unsigned, r); }
; DI float shflx(float v, int mask, int lane) { return __int_as_float(__builtin_amdgcn_ds_bpermute((lane ^ mask) << 2, __float_as_int(v))); }
; template <bool MASKED>
; DI void attnB_tile_math(const f32x16& S, int kpos0, int kvalid, int qpos, int h, int lane, float& later, unsigned (&pw)[8]) {
;     ...
;     for (int r = 0; r < 16; ++r) {
;         const float x = S[r] * scale2; x2[r] = x;
;         const float e = __builtin_amdgcn_exp2f(-fabsf(x));
;         const float v = fmaxf(x, 0.f) + __builtin_amdgcn_logf(1.0f + e);
;         if (MASKED) { const int row = (r & 3) + 8 * (r >> 2) + 4 * h; const bool vis = (row < kvalid) && (kpos0 + row < qpos); sp[r] = vis ? v : 0.f; }
;         else sp[r] = v;
;     }
;     float G[4], P[4];
; #pragma unroll
;     for (int g = 0; g < 4; ++g) { G[g] = (sp[4 * g] + sp[4 * g + 1]) + (sp[4 * g + 2] + sp[4 * g + 3]); P[g] = shflx(G[g], 32, lane); }
;     float R[4]; R[3] = 0.f; R[2] = G[3] + P[3]; R[1] = R[2] + (G[2] + P[2]); R[0] = R[1] + (G[1] + P[1]);
;     const float total = R[0] + (G[0] + P[0]);
; #pragma unroll
;     for (int g = 0; g < 4; ++g) {
;         float sfx = later + R[g] + (h == 0 ? P[g] : 0.f); float wv[4];
; #pragma unroll
;         for (int i = 3; i >= 0; --i) {
;             const int r = 4 * g + i;
;             sfx += sp[r];
;             float t = __builtin_amdgcn_exp2f(x2[r] - sfx);
;             if (MASKED) { const int row = (r & 3) + 8 * (r >> 2) + 4 * h; const bool vis = (row < kvalid) && (kpos0 + row < qpos); t = vis ? t : 0.f; }
;             wv[i] = t;
;         }
;         pw[2 * g] = pk2(wv[0], wv[1]); pw[2 * g + 1] = pk2(wv[2], wv[3]);
;     }
	v_add_f32_e32 v210, v210, v212
	v_add_f32_e32 v211, v211, v213
	v_add_f32_e32 v148, v152, v208
	v_add_f32_e32 v149, v153, v209
	s_waitcnt lgkmcnt(0)
	v_add_f32_e32 v222, v146, v150
	v_add_f32_e32 v223, v147, v151
	v_add_f32_e32 v152, v148, v210
	v_add_f32_e32 v153, v149, v211
	v_cndmask_b32_e64 v151, 0, v151, s[36:37]
	v_add_f32_e32 v222, v222, v152
	v_add_f32_e32 v223, v223, v153
	ds_bpermute_b32 v208, v184, v222
	v_add_f32_e32 v147, v189, v223
	s_mov_b64 s[10:11], 0
	s_waitcnt lgkmcnt(0)
	v_cndmask_b32_e64 v149, 0, v208, s[36:37]
	v_add_f32_e32 v147, v149, v147
	v_add_f32_e32 v147, v210, v147
	v_fma_f32 v149, v69, s16, -v147
	v_add_f32_e32 v147, v148, v147
	v_fma_f32 v148, v68, s16, -v147
	v_add_f32_e32 v147, v150, v147
	v_fma_f32 v150, v67, s16, -v147
	v_add_f32_e32 v146, v146, v147
	v_add_f32_e32 v147, v189, v153
	v_add_f32_e32 v147, v151, v147
	v_add_f32_e32 v147, v217, v147
	v_fma_f32 v151, v73, s16, -v147
	v_add_f32_e32 v147, v216, v147
	v_fma_f32 v146, v66, s16, -v146
	v_fma_f32 v152, v72, s16, -v147
	v_exp_f32_e32 v149, v149
	v_exp_f32_e32 v148, v148
	v_exp_f32_e32 v150, v150
	v_exp_f32_e32 v146, v146
	v_exp_f32_e32 v151, v151
	v_add_f32_e32 v147, v215, v147
	v_exp_f32_e32 v152, v152
	v_fma_f32 v153, v71, s16, -v147
	v_add_f32_e32 v147, v214, v147
	v_fma_f32 v147, v70, s16, -v147
	v_exp_f32_e32 v153, v153
	v_exp_f32_e32 v210, v147
	v_cvt_pk_bf16_f32 v146, v146, v150
	v_cvt_pk_bf16_f32 v147, v148, v149
	v_cvt_pk_bf16_f32 v149, v152, v151
	v_add_f32_e32 v150, v189, v211
	v_cndmask_b32_e64 v151, 0, v209, s[36:37]
	v_cndmask_b32_e64 v209, 0, v213, s[36:37]
	v_add_f32_e32 v150, v151, v150
	v_add_f32_e32 v209, v191, v209
	v_add_f32_e32 v150, v221, v150
	v_add_f32_e32 v209, v227, v209
	v_cvt_pk_bf16_f32 v148, v210, v153
	v_fma_f32 v151, v77, s16, -v150
	v_add_f32_e32 v150, v219, v150
	v_fma_f32 v210, v81, s16, -v209
	v_add_f32_e32 v209, v225, v209
	v_fma_f32 v152, v76, s16, -v150
	v_add_f32_e32 v150, v220, v150
	v_fma_f32 v211, v80, s16, -v209
	v_add_f32_e32 v209, v226, v209
	v_fma_f32 v153, v75, s16, -v150
	v_add_f32_e32 v150, v218, v150
	v_fma_f32 v212, v79, s16, -v209
	v_add_f32_e32 v209, v224, v209
	v_fma_f32 v150, v74, s16, -v150
	v_fma_f32 v209, v78, s16, -v209
	v_exp_f32_e32 v151, v151
	v_exp_f32_e32 v152, v152
	v_exp_f32_e32 v153, v153
	v_exp_f32_e32 v150, v150
	v_exp_f32_e32 v210, v210
	v_exp_f32_e32 v212, v212
	v_exp_f32_e32 v209, v209
	v_exp_f32_e32 v211, v211
	v_add_f32_e32 v208, v222, v208
	v_cvt_pk_bf16_f32 v150, v150, v153
	v_cvt_pk_bf16_f32 v151, v152, v151
	v_cvt_pk_bf16_f32 v152, v209, v212
	v_cvt_pk_bf16_f32 v153, v211, v210
	v_add_f32_e32 v208, v208, v223
.LBB0_153:
	s_andn2_b64 vcc, exec, s[10:11]
	s_cbranch_vccnz .LBB0_155
	v_exp_f32_e64 v146, -|v207|
	s_lshl_b32 s10, s30, 5
	s_or_b32 s10, s10, 16
	s_and_b64 s[8:9], s[8:9], exec
	v_add_f32_e32 v146, 1.0, v146
	v_log_f32_e32 v146, v146
	v_exp_f32_e64 v148, -|v206|
	s_cselect_b32 s8, 0, s10
	s_cselect_b32 s9, 16, 32
	v_subrev_u32_e32 v147, s8, v179
	v_min_i32_e32 v218, s9, v147
	v_max_f32_e32 v147, 0, v207
	v_add_f32_e32 v146, v147, v146
	v_add_f32_e32 v147, 1.0, v148
	v_exp_f32_e64 v148, -|v205|
	v_log_f32_e32 v147, v147
	v_max_f32_e32 v149, 0, v206
	v_exp_f32_e64 v150, -|v204|
	v_add_f32_e32 v148, 1.0, v148
	v_add_f32_e32 v147, v149, v147
	v_log_f32_e32 v149, v148
	v_cmp_lt_i32_e64 s[38:39], v185, v218
	v_cmp_lt_i32_e64 s[40:41], v186, v218
	v_cmp_lt_i32_e64 s[42:43], v187, v218
	v_cndmask_b32_e64 v148, 0, v147, s[38:39]
	v_max_f32_e32 v147, 0, v205
	v_add_f32_e32 v147, v147, v149
	v_add_f32_e32 v149, 1.0, v150
	v_log_f32_e32 v149, v149
	v_cndmask_b32_e64 v150, 0, v147, s[40:41]
	v_max_f32_e32 v147, 0, v204
	v_max_f32_e32 v204, 0, v203
	v_add_f32_e32 v147, v147, v149
	v_exp_f32_e64 v149, -|v203|
	v_cndmask_b32_e64 v152, 0, v147, s[42:43]
	v_exp_f32_e64 v147, -|v202|
	v_max_f32_e32 v205, 0, v201
	v_add_f32_e32 v149, 1.0, v149
	v_log_f32_e32 v206, v149
	v_add_f32_e32 v147, 1.0, v147
	v_exp_f32_e64 v149, -|v201|
	v_log_f32_e32 v208, v147
	v_exp_f32_e64 v147, -|v200|
	v_max_f32_e32 v203, 0, v200
	v_add_f32_e32 v149, 1.0, v149
	v_log_f32_e32 v207, v149
	v_add_f32_e32 v147, 1.0, v147
	v_exp_f32_e64 v149, -|v199|
	v_log_f32_e32 v209, v147
	v_exp_f32_e64 v147, -|v198|
	v_max_f32_e32 v200, 0, v199
	v_add_f32_e32 v149, 1.0, v149
	v_log_f32_e32 v210, v149
	v_add_f32_e32 v147, 1.0, v147
	v_exp_f32_e64 v149, -|v197|
	v_log_f32_e32 v212, v147
	v_exp_f32_e64 v147, -|v196|
	v_max_f32_e32 v201, 0, v197
	v_add_f32_e32 v149, 1.0, v149
	v_log_f32_e32 v211, v149
	v_add_f32_e32 v147, 1.0, v147
	v_exp_f32_e64 v149, -|v195|
	v_log_f32_e32 v213, v147
	v_exp_f32_e64 v147, -|v194|
	v_max_f32_e32 v199, 0, v196
	v_add_f32_e32 v149, 1.0, v149
	v_log_f32_e32 v214, v149
	v_add_f32_e32 v147, 1.0, v147
	v_exp_f32_e64 v149, -|v193|
	v_max_f32_e32 v196, 0, v195
	v_log_f32_e32 v216, v147
	v_max_f32_e32 v197, 0, v193
	v_exp_f32_e64 v147, -|v192|
	v_max_f32_e32 v195, 0, v192
	v_add_f32_e32 v192, v204, v206
	v_add_f32_e32 v193, v205, v207
	v_cmp_lt_i32_e64 s[44:45], v163, v218
	v_max_f32_e32 v202, 0, v202
	v_add_f32_e32 v202, v202, v208
	v_add_f32_e32 v203, v203, v209
	v_cndmask_b32_e64 v193, 0, v193, s[44:45]
	v_cmp_lt_i32_e64 s[44:45], v0, v218
	v_add_f32_e32 v149, 1.0, v149
	v_log_f32_e32 v215, v149
	v_cndmask_b32_e64 v192, 0, v192, s[44:45]
	v_cmp_lt_i32_e64 s[44:45], v165, v218
	v_add_f32_e32 v200, v200, v210
	v_add_f32_e32 v201, v201, v211
	v_max_f32_e32 v198, 0, v198
	v_cndmask_b32_e64 v203, 0, v203, s[44:45]
	v_cmp_lt_i32_e64 s[44:45], v162, v218
	v_add_f32_e32 v147, 1.0, v147
	v_log_f32_e32 v217, v147
	v_cndmask_b32_e64 v202, 0, v202, s[44:45]
	v_cmp_lt_i32_e64 s[44:45], v167, v218
	v_add_f32_e32 v198, v198, v212
	v_add_f32_e32 v199, v199, v213
	v_add_f32_e32 v196, v196, v214
	v_add_f32_e32 v197, v197, v215
	v_cndmask_b32_e64 v201, 0, v201, s[44:45]
	v_cmp_lt_i32_e64 s[44:45], v164, v218
	v_max_f32_e32 v194, 0, v194
	v_add_f32_e32 v194, v194, v216
	v_add_f32_e32 v195, v195, v217
	v_cndmask_b32_e64 v200, 0, v200, s[44:45]
	v_cmp_lt_i32_e64 s[44:45], v169, v218
	v_cmp_lt_i32_e32 vcc, v183, v218
	s_nop 0
	v_cndmask_b32_e64 v199, 0, v199, s[44:45]
	v_cmp_lt_i32_e64 s[44:45], v166, v218
	v_cndmask_b32_e32 v146, 0, v146, vcc
	s_nop 0
	v_cndmask_b32_e64 v198, 0, v198, s[44:45]
	v_cmp_lt_i32_e64 s[44:45], v171, v218
	v_add_f32_e32 v204, v200, v198
	v_add_f32_e32 v205, v201, v199
	s_nop 0
	v_cndmask_b32_e64 v197, 0, v197, s[44:45]
	v_cmp_lt_i32_e64 s[44:45], v168, v218
	v_add_f32_e32 v147, v204, v205
	ds_bpermute_b32 v209, v184, v147
	v_cndmask_b32_e64 v196, 0, v196, s[44:45]
	v_cmp_lt_i32_e64 s[44:45], v173, v218
	s_nop 1
	v_cndmask_b32_e64 v195, 0, v195, s[44:45]
	v_cmp_lt_i32_e64 s[44:45], v170, v218
	s_nop 1
	v_cndmask_b32_e64 v194, 0, v194, s[44:45]
	v_add_f32_e32 v204, v196, v194
	v_add_f32_e32 v205, v197, v195
	s_nop 0
	v_add_f32_e32 v151, v204, v205
	v_add_f32_e32 v204, v192, v202
	v_add_f32_e32 v205, v193, v203
	ds_bpermute_b32 v208, v184, v151
	v_add_f32_e32 v204, v204, v205
	v_mov_b32_e32 v205, v204
	ds_bpermute_b32 v149, v184, v204
	s_waitcnt lgkmcnt(1)
; DI unsigned pk2(float a, float b) { f32x2 v = {a, b}; bf16v2 r = __builtin_convertvector(v, bf16v2); return __builtin_bit_cast(unsigned, r); }
; template <bool MASKED>
; DI void attnB_tile_math(const f32x16& S, int kpos0, int kvalid, int qpos, int h, int lane, float& later, unsigned (&pw)[8]) {
;     ...
;     for (int g = 0; g < 4; ++g) {
;         float sfx = later + R[g] + (h == 0 ? P[g] : 0.f); float wv[4];
; #pragma unroll
;         for (int i = 3; i >= 0; --i) {
;             const int r = 4 * g + i;
;             sfx += sp[r];
;             float t = __builtin_amdgcn_exp2f(x2[r] - sfx);
;             if (MASKED) { const int row = (r & 3) + 8 * (r >> 2) + 4 * h; const bool vis = (row < kvalid) && (kpos0 + row < qpos); t = vis ? t : 0.f; }
;             wv[i] = t;
;         }
;         pw[2 * g] = pk2(wv[0], wv[1]); pw[2 * g + 1] = pk2(wv[2], wv[3]);
;     }
;     later += total;
	v_add_f32_e32 v153, v151, v208
	v_add_f32_e32 v151, v147, v209
	v_mov_b32_e32 v147, v204
	v_add_f32_e32 v206, v150, v152
	v_add_f32_e32 v207, v151, v153
	s_waitcnt lgkmcnt(0)
	v_add_f32_e32 v204, v146, v148
	v_add_f32_e32 v205, v147, v149
	s_nop 0
	v_add_f32_e32 v204, v204, v206
	v_add_f32_e32 v205, v205, v207
	ds_bpermute_b32 v206, v184, v204
	v_add_f32_e32 v147, v189, v205
	s_waitcnt lgkmcnt(0)
	v_cndmask_b32_e64 v151, 0, v206, s[36:37]
	v_add_f32_e32 v147, v151, v147
	v_add_f32_e32 v147, v152, v147
	v_fma_f32 v69, v69, s16, -v147
	v_add_f32_e32 v147, v150, v147
	v_fma_f32 v68, v68, s16, -v147
	v_add_f32_e32 v147, v148, v147
	v_add_f32_e32 v146, v146, v147
	v_fma_f32 v67, v67, s16, -v147
	v_fma_f32 v66, v66, s16, -v146
	v_exp_f32_e32 v67, v67
	v_exp_f32_e32 v66, v66
	v_exp_f32_e32 v69, v69
	v_exp_f32_e32 v68, v68
	v_cndmask_b32_e64 v67, 0, v67, s[38:39]
	v_cndmask_b32_e32 v66, 0, v66, vcc
	v_cvt_pk_bf16_f32 v146, v66, v67
	v_add_f32_e32 v66, v189, v207
	v_cndmask_b32_e64 v67, 0, v149, s[36:37]
	v_add_f32_e32 v66, v67, v66
	v_add_f32_e32 v66, v203, v66
	v_cndmask_b32_e64 v69, 0, v69, s[42:43]
	v_cndmask_b32_e64 v68, 0, v68, s[40:41]
	v_fma_f32 v67, v73, s16, -v66
	v_add_f32_e32 v66, v193, v66
	v_cvt_pk_bf16_f32 v147, v68, v69
	v_exp_f32_e32 v67, v67
	v_fma_f32 v68, v72, s16, -v66
	v_add_f32_e32 v66, v202, v66
	v_exp_f32_e32 v68, v68
	v_fma_f32 v69, v71, s16, -v66
	v_add_f32_e32 v66, v192, v66
	v_exp_f32_e32 v69, v69
	v_fma_f32 v66, v70, s16, -v66
	v_cmp_gt_i32_e32 vcc, v218, v165
	v_exp_f32_e32 v66, v66
	s_nop 0
	v_cndmask_b32_e32 v67, 0, v67, vcc
	v_cmp_gt_i32_e32 vcc, v218, v163
	s_nop 1
	v_cndmask_b32_e32 v68, 0, v68, vcc
	v_cmp_gt_i32_e32 vcc, v218, v162
	v_cvt_pk_bf16_f32 v149, v68, v67
	v_cndmask_b32_e64 v67, 0, v209, s[36:37]
	v_cndmask_b32_e32 v69, 0, v69, vcc
	v_cmp_gt_i32_e32 vcc, v218, v0
	s_nop 1
	v_cndmask_b32_e32 v66, 0, v66, vcc
	v_cvt_pk_bf16_f32 v148, v66, v69
	v_add_f32_e32 v66, v189, v153
	v_add_f32_e32 v66, v67, v66
	v_add_f32_e32 v66, v199, v66
	v_fma_f32 v67, v77, s16, -v66
	v_add_f32_e32 v66, v201, v66
	v_exp_f32_e32 v67, v67
	v_fma_f32 v68, v76, s16, -v66
	v_add_f32_e32 v66, v198, v66
	v_exp_f32_e32 v68, v68
	v_fma_f32 v69, v75, s16, -v66
	v_add_f32_e32 v66, v200, v66
	v_exp_f32_e32 v69, v69
	v_fma_f32 v66, v74, s16, -v66
	v_cmp_gt_i32_e32 vcc, v218, v169
	v_exp_f32_e32 v66, v66
	s_nop 0
	v_cndmask_b32_e32 v67, 0, v67, vcc
	v_cmp_gt_i32_e32 vcc, v218, v167
	s_nop 1
	v_cndmask_b32_e32 v68, 0, v68, vcc
	v_cmp_gt_i32_e32 vcc, v218, v166
	v_cvt_pk_bf16_f32 v151, v68, v67
	s_nop 0
	v_cndmask_b32_e32 v69, 0, v69, vcc
	v_cmp_gt_i32_e32 vcc, v218, v164
	s_nop 1
	v_cndmask_b32_e32 v66, 0, v66, vcc
	v_cvt_pk_bf16_f32 v150, v66, v69
	v_cndmask_b32_e64 v66, 0, v208, s[36:37]
	v_add_f32_e32 v66, v191, v66
	v_add_f32_e32 v66, v195, v66
	v_add_f32_e32 v67, v197, v66
	v_add_f32_e32 v68, v194, v67
	v_add_f32_e32 v69, v196, v68
	v_fma_f32 v69, v78, s16, -v69
	v_exp_f32_e32 v69, v69
	v_fma_f32 v68, v79, s16, -v68
	v_exp_f32_e32 v68, v68
	v_fma_f32 v67, v80, s16, -v67
	v_exp_f32_e32 v67, v67
	v_fma_f32 v66, v81, s16, -v66
	v_cmp_gt_i32_e32 vcc, v218, v168
	v_exp_f32_e32 v66, v66
	s_nop 0
	v_cndmask_b32_e32 v69, 0, v69, vcc
	v_cmp_gt_i32_e32 vcc, v218, v170
	s_nop 1
	v_cndmask_b32_e32 v68, 0, v68, vcc
	v_cmp_gt_i32_e32 vcc, v218, v171
	v_cvt_pk_bf16_f32 v152, v69, v68
	s_nop 0
	v_cndmask_b32_e32 v67, 0, v67, vcc
	v_cmp_gt_i32_e32 vcc, v218, v173
	s_nop 1
	v_cndmask_b32_e32 v66, 0, v66, vcc
	v_cvt_pk_bf16_f32 v153, v67, v66
	v_add_f32_e32 v66, v204, v206
	v_add_f32_e32 v208, v66, v205

; DI void attnA_item(bf16_t* z, const float* sinks, int hp, int qs, LAS bf16_t* vs, const LAS float* btab, int lane) {
;     ...
;             if (resc) {
; #pragma unroll
;                 for (int dt = 0; dt < 2; ++dt)
; #pragma unroll
;                     for (int i = 0; i < 16; ++i) acc[u][dt][i] *= corr;
;             }
.LBB0_201:
	s_andn2_b64 vcc, exec, s[4:5]
	s_cbranch_vccnz .LBB0_203
	v_mul_f32_e32 v64, v64, v0
	v_mul_f32_e32 v65, v65, v0
	v_mul_f32_e32 v62, v62, v0
	v_mul_f32_e32 v63, v63, v0
	v_mul_f32_e32 v60, v60, v0
	v_mul_f32_e32 v61, v61, v0
	v_mul_f32_e32 v58, v58, v0
	v_mul_f32_e32 v59, v59, v0
	v_mul_f32_e32 v56, v56, v0
	v_mul_f32_e32 v57, v57, v0
	v_mul_f32_e32 v54, v54, v0
	v_mul_f32_e32 v55, v55, v0
	v_mul_f32_e32 v52, v52, v0
	v_mul_f32_e32 v53, v53, v0
	v_mul_f32_e32 v50, v50, v0
	v_mul_f32_e32 v51, v51, v0
	v_mul_f32_e32 v48, v48, v0
	v_mul_f32_e32 v49, v49, v0
	v_mul_f32_e32 v46, v46, v0
	v_mul_f32_e32 v47, v47, v0
	v_mul_f32_e32 v44, v44, v0
	v_mul_f32_e32 v45, v45, v0
	v_mul_f32_e32 v42, v42, v0
	v_mul_f32_e32 v43, v43, v0
	v_mul_f32_e32 v40, v40, v0
	v_mul_f32_e32 v41, v41, v0
	v_mul_f32_e32 v38, v38, v0
	v_mul_f32_e32 v39, v39, v0
	v_mul_f32_e32 v36, v36, v0
	v_mul_f32_e32 v37, v37, v0
	v_mul_f32_e32 v34, v34, v0
	v_mul_f32_e32 v35, v35, v0

; DI void attnA_item(bf16_t* z, const float* sinks, int hp, int qs, LAS bf16_t* vs, const LAS float* btab, int lane) {
;     ...
;             if (resc) {
; #pragma unroll
;                 for (int dt = 0; dt < 2; ++dt)
; #pragma unroll
;                     for (int i = 0; i < 16; ++i) acc[u][dt][i] *= corr;
;             }
.LBB0_206:
	v_mul_f32_e32 v32, v32, v66
	v_mul_f32_e32 v33, v33, v66
	v_mul_f32_e32 v30, v30, v66
	v_mul_f32_e32 v31, v31, v66
	v_mul_f32_e32 v28, v28, v66
	v_mul_f32_e32 v29, v29, v66
	v_mul_f32_e32 v26, v26, v66
	v_mul_f32_e32 v27, v27, v66
	v_mul_f32_e32 v24, v24, v66
	v_mul_f32_e32 v25, v25, v66
	v_mul_f32_e32 v22, v22, v66
	v_mul_f32_e32 v23, v23, v66
	v_mul_f32_e32 v20, v20, v66
	v_mul_f32_e32 v21, v21, v66
	v_mul_f32_e32 v18, v18, v66
	v_mul_f32_e32 v19, v19, v66
	v_mul_f32_e32 v16, v16, v66
	v_mul_f32_e32 v17, v17, v66
	v_mul_f32_e32 v14, v14, v66
	v_mul_f32_e32 v15, v15, v66
	v_mul_f32_e32 v12, v12, v66
	v_mul_f32_e32 v13, v13, v66
	v_mul_f32_e32 v10, v10, v66
	v_mul_f32_e32 v11, v11, v66
	v_mul_f32_e32 v8, v8, v66
	v_mul_f32_e32 v9, v9, v66
	v_mul_f32_e32 v6, v6, v66
	v_mul_f32_e32 v7, v7, v66
	v_mul_f32_e32 v4, v4, v66
	v_mul_f32_e32 v5, v5, v66
	v_mul_f32_e32 v2, v2, v66
	v_mul_f32_e32 v3, v3, v66
